# P10 gnorm loop rewritten: 4 chunks/iter, prefetch next batch, DPP row reductions
# speedup vs baseline: 1.0180x; 1.0180x over previous
.LBB0_1415:
	s_or_b64 exec, exec, s[0:1]
	s_waitcnt lgkmcnt(0)
	v_mov_b32_e32 v0, v198
	s_barrier
	v_readlane_b32 s0, v254, 29
	s_waitcnt vmcnt(29)
	v_ashrrev_i32_e32 v8, 6, v0
	v_add_u32_e32 v1, s0, v8
	s_mov_b32 s0, 0x11000
	v_cmp_gt_i32_e32 vcc, s0, v1
	s_and_saveexec_b64 s[0:1], vcc
	v_readlane_b32 s16, v254, 27
	v_readlane_b32 s17, v254, 28
	s_cbranch_execz .LBB0_1418
	s_add_u32 s60, s94, 0x2a402800
	s_addc_u32 s61, s95, 0
	s_add_u32 s62, s94, 0x1ec02800
	s_addc_u32 s63, s95, 0
	s_add_u32 s64, s94, 0x16402800
	s_addc_u32 s65, s95, 0
	v_lshrrev_b32_e32 v1, 6, v198
	v_and_b32_e32 v0, 63, v198
	v_readfirstlane_b32 s66, v1
	v_lshlrev_b32_e32 v0, 4, v0
	v_mov_b32_e32 v9, 0x358637bd
	s_nop 3
	s_lshl_b32 s70, s2, 3
	s_add_u32 s66, s66, s70
	s_mov_b32 s67, 0x11000
	s_mov_b32 s68, s16
	s_lshl_b32 s69, s16, 2
	s_add_u32 s71, s66, s68
	s_add_u32 s72, s71, s68
	s_add_u32 s73, s72, s68
	s_cmp_lt_u32 s71, s67
	s_cselect_b32 s71, s71, s66
	s_cmp_lt_u32 s72, s67
	s_cselect_b32 s72, s72, s66
	s_cmp_lt_u32 s73, s67
	s_cselect_b32 s73, s73, s66
	s_lshl_b32 s74, s66, 10
	s_lshl_b32 s75, s71, 10
	s_lshl_b32 s76, s72, 10
	s_lshl_b32 s77, s73, 10
	v_add_u32_e32 v1, s74, v0
	v_add_u32_e32 v2, s75, v0
	v_add_u32_e32 v3, s76, v0
	v_add_u32_e32 v4, s77, v0
	global_load_dwordx4 v[16:19], v1, s[60:61]
	global_load_dwordx4 v[20:23], v1, s[62:63]
	global_load_dwordx4 v[24:27], v2, s[60:61]
	global_load_dwordx4 v[28:31], v2, s[62:63]
	global_load_dwordx4 v[32:35], v3, s[60:61]
	global_load_dwordx4 v[36:39], v3, s[62:63]
	global_load_dwordx4 v[40:43], v4, s[60:61]
	global_load_dwordx4 v[44:47], v4, s[62:63]
	s_waitcnt vmcnt(0)
.Lgn_top:
	v_lshlrev_b32_e32 v48, 16, v16
	v_and_b32_e32 v49, 0xffff0000, v16
	v_lshlrev_b32_e32 v50, 16, v17
	v_and_b32_e32 v51, 0xffff0000, v17
	v_lshlrev_b32_e32 v52, 16, v18
	v_and_b32_e32 v53, 0xffff0000, v18
	v_lshlrev_b32_e32 v54, 16, v19
	v_and_b32_e32 v55, 0xffff0000, v19
	v_mov_b64_e32 v[80:81], v[20:21]
	v_mov_b64_e32 v[82:83], v[22:23]
	v_mov_b32_e32 v5, v1
	v_lshlrev_b32_e32 v56, 16, v24
	v_and_b32_e32 v57, 0xffff0000, v24
	v_lshlrev_b32_e32 v58, 16, v25
	v_and_b32_e32 v59, 0xffff0000, v25
	v_lshlrev_b32_e32 v60, 16, v26
	v_and_b32_e32 v61, 0xffff0000, v26
	v_lshlrev_b32_e32 v62, 16, v27
	v_and_b32_e32 v63, 0xffff0000, v27
	v_mov_b64_e32 v[84:85], v[28:29]
	v_mov_b64_e32 v[86:87], v[30:31]
	v_mov_b32_e32 v6, v2
	v_lshlrev_b32_e32 v64, 16, v32
	v_and_b32_e32 v65, 0xffff0000, v32
	v_lshlrev_b32_e32 v66, 16, v33
	v_and_b32_e32 v67, 0xffff0000, v33
	v_lshlrev_b32_e32 v68, 16, v34
	v_and_b32_e32 v69, 0xffff0000, v34
	v_lshlrev_b32_e32 v70, 16, v35
	v_and_b32_e32 v71, 0xffff0000, v35
	v_mov_b64_e32 v[88:89], v[36:37]
	v_mov_b64_e32 v[90:91], v[38:39]
	v_mov_b32_e32 v7, v3
	v_lshlrev_b32_e32 v72, 16, v40
	v_and_b32_e32 v73, 0xffff0000, v40
	v_lshlrev_b32_e32 v74, 16, v41
	v_and_b32_e32 v75, 0xffff0000, v41
	v_lshlrev_b32_e32 v76, 16, v42
	v_and_b32_e32 v77, 0xffff0000, v42
	v_lshlrev_b32_e32 v78, 16, v43
	v_and_b32_e32 v79, 0xffff0000, v43
	v_mov_b64_e32 v[92:93], v[44:45]
	v_mov_b64_e32 v[94:95], v[46:47]
	v_mov_b32_e32 v8, v4
	s_add_u32 s70, s66, s69
	s_cmp_lt_u32 s70, s67
	s_cbranch_scc0 .Lgn_noload
	s_add_u32 s71, s70, s68
	s_add_u32 s72, s71, s68
	s_add_u32 s73, s72, s68
	s_cmp_lt_u32 s71, s67
	s_cselect_b32 s71, s71, s70
	s_cmp_lt_u32 s72, s67
	s_cselect_b32 s72, s72, s70
	s_cmp_lt_u32 s73, s67
	s_cselect_b32 s73, s73, s70
	s_lshl_b32 s74, s70, 10
	s_lshl_b32 s75, s71, 10
	s_lshl_b32 s76, s72, 10
	s_lshl_b32 s77, s73, 10
	v_add_u32_e32 v1, s74, v0
	v_add_u32_e32 v2, s75, v0
	v_add_u32_e32 v3, s76, v0
	v_add_u32_e32 v4, s77, v0
	global_load_dwordx4 v[16:19], v1, s[60:61]
	global_load_dwordx4 v[20:23], v1, s[62:63]
	global_load_dwordx4 v[24:27], v2, s[60:61]
	global_load_dwordx4 v[28:31], v2, s[62:63]
	global_load_dwordx4 v[32:35], v3, s[60:61]
	global_load_dwordx4 v[36:39], v3, s[62:63]
	global_load_dwordx4 v[40:43], v4, s[60:61]
	global_load_dwordx4 v[44:47], v4, s[62:63]
.Lgn_noload:
	v_add_f32_e32 v96, v48, v49
	v_add_f32_e32 v112, v50, v51
	v_add_f32_e32 v113, v52, v53
	v_add_f32_e32 v114, v54, v55
	v_add_f32_e32 v96, v96, v112
	v_add_f32_e32 v113, v113, v114
	v_add_f32_e32 v96, v96, v113
	v_add_f32_e32 v97, v56, v57
	v_add_f32_e32 v116, v58, v59
	v_add_f32_e32 v117, v60, v61
	v_add_f32_e32 v118, v62, v63
	v_add_f32_e32 v97, v97, v116
	v_add_f32_e32 v117, v117, v118
	v_add_f32_e32 v97, v97, v117
	v_add_f32_e32 v98, v64, v65
	v_add_f32_e32 v120, v66, v67
	v_add_f32_e32 v121, v68, v69
	v_add_f32_e32 v122, v70, v71
	v_add_f32_e32 v98, v98, v120
	v_add_f32_e32 v121, v121, v122
	v_add_f32_e32 v98, v98, v121
	v_add_f32_e32 v99, v72, v73
	v_add_f32_e32 v124, v74, v75
	v_add_f32_e32 v125, v76, v77
	v_add_f32_e32 v126, v78, v79
	v_add_f32_e32 v99, v99, v124
	v_add_f32_e32 v125, v125, v126
	v_add_f32_e32 v99, v99, v125
	s_nop 1
	v_add_f32_dpp v96, v96, v96 quad_perm:[1,0,3,2] row_mask:0xf bank_mask:0xf
	v_add_f32_dpp v97, v97, v97 quad_perm:[1,0,3,2] row_mask:0xf bank_mask:0xf
	v_add_f32_dpp v98, v98, v98 quad_perm:[1,0,3,2] row_mask:0xf bank_mask:0xf
	v_add_f32_dpp v99, v99, v99 quad_perm:[1,0,3,2] row_mask:0xf bank_mask:0xf
	v_add_f32_dpp v96, v96, v96 quad_perm:[2,3,0,1] row_mask:0xf bank_mask:0xf
	v_add_f32_dpp v97, v97, v97 quad_perm:[2,3,0,1] row_mask:0xf bank_mask:0xf
	v_add_f32_dpp v98, v98, v98 quad_perm:[2,3,0,1] row_mask:0xf bank_mask:0xf
	v_add_f32_dpp v99, v99, v99 quad_perm:[2,3,0,1] row_mask:0xf bank_mask:0xf
	v_add_f32_dpp v96, v96, v96 row_half_mirror row_mask:0xf bank_mask:0xf
	v_add_f32_dpp v97, v97, v97 row_half_mirror row_mask:0xf bank_mask:0xf
	v_add_f32_dpp v98, v98, v98 row_half_mirror row_mask:0xf bank_mask:0xf
	v_add_f32_dpp v99, v99, v99 row_half_mirror row_mask:0xf bank_mask:0xf
	v_add_f32_dpp v96, v96, v96 row_mirror row_mask:0xf bank_mask:0xf
	v_add_f32_dpp v97, v97, v97 row_mirror row_mask:0xf bank_mask:0xf
	v_add_f32_dpp v98, v98, v98 row_mirror row_mask:0xf bank_mask:0xf
	v_add_f32_dpp v99, v99, v99 row_mirror row_mask:0xf bank_mask:0xf
	s_nop 0
	v_readlane_b32 s78, v96, 0
	v_readlane_b32 s79, v96, 16
	v_readlane_b32 s80, v96, 32
	v_readlane_b32 s81, v96, 48
	v_readlane_b32 s82, v97, 0
	v_readlane_b32 s83, v97, 16
	v_readlane_b32 s84, v97, 32
	v_readlane_b32 s85, v97, 48
	s_nop 0
	v_mov_b32_e32 v104, s78
	v_mov_b32_e32 v106, s82
	v_add_f32_e32 v104, s79, v104
	v_add_f32_e32 v106, s83, v106
	v_add_f32_e32 v104, s80, v104
	v_add_f32_e32 v106, s84, v106
	v_add_f32_e32 v104, s81, v104
	v_add_f32_e32 v106, s85, v106
	v_readlane_b32 s78, v98, 0
	v_readlane_b32 s79, v98, 16
	v_readlane_b32 s80, v98, 32
	v_readlane_b32 s81, v98, 48
	v_readlane_b32 s82, v99, 0
	v_readlane_b32 s83, v99, 16
	v_readlane_b32 s84, v99, 32
	v_readlane_b32 s85, v99, 48
	s_nop 0
	v_mov_b32_e32 v108, s78
	v_mov_b32_e32 v110, s82
	v_add_f32_e32 v108, s79, v108
	v_add_f32_e32 v110, s83, v110
	v_add_f32_e32 v108, s80, v108
	v_add_f32_e32 v110, s84, v110
	v_add_f32_e32 v108, s81, v108
	v_add_f32_e32 v110, s85, v110
	v_fmac_f32_e32 v48, 0xbb000000, v104
	v_fmac_f32_e32 v49, 0xbb000000, v104
	v_fmac_f32_e32 v50, 0xbb000000, v104
	v_fmac_f32_e32 v51, 0xbb000000, v104
	v_fmac_f32_e32 v52, 0xbb000000, v104
	v_fmac_f32_e32 v53, 0xbb000000, v104
	v_fmac_f32_e32 v54, 0xbb000000, v104
	v_fmac_f32_e32 v55, 0xbb000000, v104
	v_fmac_f32_e32 v56, 0xbb000000, v106
	v_fmac_f32_e32 v57, 0xbb000000, v106
	v_fmac_f32_e32 v58, 0xbb000000, v106
	v_fmac_f32_e32 v59, 0xbb000000, v106
	v_fmac_f32_e32 v60, 0xbb000000, v106
	v_fmac_f32_e32 v61, 0xbb000000, v106
	v_fmac_f32_e32 v62, 0xbb000000, v106
	v_fmac_f32_e32 v63, 0xbb000000, v106
	v_fmac_f32_e32 v64, 0xbb000000, v108
	v_fmac_f32_e32 v65, 0xbb000000, v108
	v_fmac_f32_e32 v66, 0xbb000000, v108
	v_fmac_f32_e32 v67, 0xbb000000, v108
	v_fmac_f32_e32 v68, 0xbb000000, v108
	v_fmac_f32_e32 v69, 0xbb000000, v108
	v_fmac_f32_e32 v70, 0xbb000000, v108
	v_fmac_f32_e32 v71, 0xbb000000, v108
	v_fmac_f32_e32 v72, 0xbb000000, v110
	v_fmac_f32_e32 v73, 0xbb000000, v110
	v_fmac_f32_e32 v74, 0xbb000000, v110
	v_fmac_f32_e32 v75, 0xbb000000, v110
	v_fmac_f32_e32 v76, 0xbb000000, v110
	v_fmac_f32_e32 v77, 0xbb000000, v110
	v_fmac_f32_e32 v78, 0xbb000000, v110
	v_fmac_f32_e32 v79, 0xbb000000, v110
	v_mul_f32_e32 v96, v48, v48
	v_mul_f32_e32 v112, v49, v49
	v_fmac_f32_e32 v96, v50, v50
	v_fmac_f32_e32 v112, v51, v51
	v_fmac_f32_e32 v96, v52, v52
	v_fmac_f32_e32 v112, v53, v53
	v_fmac_f32_e32 v96, v54, v54
	v_fmac_f32_e32 v112, v55, v55
	v_add_f32_e32 v96, v96, v112
	v_mul_f32_e32 v97, v56, v56
	v_mul_f32_e32 v116, v57, v57
	v_fmac_f32_e32 v97, v58, v58
	v_fmac_f32_e32 v116, v59, v59
	v_fmac_f32_e32 v97, v60, v60
	v_fmac_f32_e32 v116, v61, v61
	v_fmac_f32_e32 v97, v62, v62
	v_fmac_f32_e32 v116, v63, v63
	v_add_f32_e32 v97, v97, v116
	v_mul_f32_e32 v98, v64, v64
	v_mul_f32_e32 v120, v65, v65
	v_fmac_f32_e32 v98, v66, v66
	v_fmac_f32_e32 v120, v67, v67
	v_fmac_f32_e32 v98, v68, v68
	v_fmac_f32_e32 v120, v69, v69
	v_fmac_f32_e32 v98, v70, v70
	v_fmac_f32_e32 v120, v71, v71
	v_add_f32_e32 v98, v98, v120
	v_mul_f32_e32 v99, v72, v72
	v_mul_f32_e32 v124, v73, v73
	v_fmac_f32_e32 v99, v74, v74
	v_fmac_f32_e32 v124, v75, v75
	v_fmac_f32_e32 v99, v76, v76
	v_fmac_f32_e32 v124, v77, v77
	v_fmac_f32_e32 v99, v78, v78
	v_fmac_f32_e32 v124, v79, v79
	v_add_f32_e32 v99, v99, v124
	s_nop 1
	v_add_f32_dpp v96, v96, v96 quad_perm:[1,0,3,2] row_mask:0xf bank_mask:0xf
	v_add_f32_dpp v97, v97, v97 quad_perm:[1,0,3,2] row_mask:0xf bank_mask:0xf
	v_add_f32_dpp v98, v98, v98 quad_perm:[1,0,3,2] row_mask:0xf bank_mask:0xf
	v_add_f32_dpp v99, v99, v99 quad_perm:[1,0,3,2] row_mask:0xf bank_mask:0xf
	v_add_f32_dpp v96, v96, v96 quad_perm:[2,3,0,1] row_mask:0xf bank_mask:0xf
	v_add_f32_dpp v97, v97, v97 quad_perm:[2,3,0,1] row_mask:0xf bank_mask:0xf
	v_add_f32_dpp v98, v98, v98 quad_perm:[2,3,0,1] row_mask:0xf bank_mask:0xf
	v_add_f32_dpp v99, v99, v99 quad_perm:[2,3,0,1] row_mask:0xf bank_mask:0xf
	v_add_f32_dpp v96, v96, v96 row_half_mirror row_mask:0xf bank_mask:0xf
	v_add_f32_dpp v97, v97, v97 row_half_mirror row_mask:0xf bank_mask:0xf
	v_add_f32_dpp v98, v98, v98 row_half_mirror row_mask:0xf bank_mask:0xf
	v_add_f32_dpp v99, v99, v99 row_half_mirror row_mask:0xf bank_mask:0xf
	v_add_f32_dpp v96, v96, v96 row_mirror row_mask:0xf bank_mask:0xf
	v_add_f32_dpp v97, v97, v97 row_mirror row_mask:0xf bank_mask:0xf
	v_add_f32_dpp v98, v98, v98 row_mirror row_mask:0xf bank_mask:0xf
	v_add_f32_dpp v99, v99, v99 row_mirror row_mask:0xf bank_mask:0xf
	s_nop 0
	v_readlane_b32 s78, v96, 0
	v_readlane_b32 s79, v96, 16
	v_readlane_b32 s80, v96, 32
	v_readlane_b32 s81, v96, 48
	v_readlane_b32 s82, v97, 0
	v_readlane_b32 s83, v97, 16
	v_readlane_b32 s84, v97, 32
	v_readlane_b32 s85, v97, 48
	s_nop 0
	v_mov_b32_e32 v104, s78
	v_mov_b32_e32 v106, s82
	v_add_f32_e32 v104, s79, v104
	v_add_f32_e32 v106, s83, v106
	v_add_f32_e32 v104, s80, v104
	v_add_f32_e32 v106, s84, v106
	v_add_f32_e32 v104, s81, v104
	v_add_f32_e32 v106, s85, v106
	v_readlane_b32 s78, v98, 0
	v_readlane_b32 s79, v98, 16
	v_readlane_b32 s80, v98, 32
	v_readlane_b32 s81, v98, 48
	v_readlane_b32 s82, v99, 0
	v_readlane_b32 s83, v99, 16
	v_readlane_b32 s84, v99, 32
	v_readlane_b32 s85, v99, 48
	s_nop 0
	v_mov_b32_e32 v108, s78
	v_mov_b32_e32 v110, s82
	v_add_f32_e32 v108, s79, v108
	v_add_f32_e32 v110, s83, v110
	v_add_f32_e32 v108, s80, v108
	v_add_f32_e32 v110, s84, v110
	v_add_f32_e32 v108, s81, v108
	v_add_f32_e32 v110, s85, v110
	v_fmamk_f32 v104, v104, 0x3b000000, v9
	v_fmamk_f32 v106, v106, 0x3b000000, v9
	v_fmamk_f32 v108, v108, 0x3b000000, v9
	v_fmamk_f32 v110, v110, 0x3b000000, v9
	v_rsq_f32_e32 v104, v104
	v_rsq_f32_e32 v106, v106
	v_rsq_f32_e32 v108, v108
	v_rsq_f32_e32 v110, v110
	s_nop 0
	v_lshlrev_b32_e32 v128, 16, v80
	v_and_b32_e32 v129, 0xffff0000, v80
	v_lshlrev_b32_e32 v130, 16, v81
	v_and_b32_e32 v131, 0xffff0000, v81
	v_lshlrev_b32_e32 v132, 16, v82
	v_and_b32_e32 v133, 0xffff0000, v82
	v_lshlrev_b32_e32 v134, 16, v83
	v_and_b32_e32 v135, 0xffff0000, v83
	v_pk_mul_f32 v[48:49], v[48:49], v[104:105] op_sel_hi:[1,0]
	v_pk_mul_f32 v[50:51], v[50:51], v[104:105] op_sel_hi:[1,0]
	v_pk_mul_f32 v[52:53], v[52:53], v[104:105] op_sel_hi:[1,0]
	v_pk_mul_f32 v[54:55], v[54:55], v[104:105] op_sel_hi:[1,0]
	v_pk_mul_f32 v[48:49], v[48:49], v[128:129]
	v_pk_mul_f32 v[50:51], v[50:51], v[130:131]
	v_pk_mul_f32 v[52:53], v[52:53], v[132:133]
	v_pk_mul_f32 v[54:55], v[54:55], v[134:135]
	v_cvt_pk_bf16_f32 v112, v48, v49
	v_cvt_pk_bf16_f32 v113, v50, v51
	v_cvt_pk_bf16_f32 v114, v52, v53
	v_cvt_pk_bf16_f32 v115, v54, v55
	global_store_dwordx4 v5, v[112:115], s[64:65]
	v_lshlrev_b32_e32 v128, 16, v84
	v_and_b32_e32 v129, 0xffff0000, v84
	v_lshlrev_b32_e32 v130, 16, v85
	v_and_b32_e32 v131, 0xffff0000, v85
	v_lshlrev_b32_e32 v132, 16, v86
	v_and_b32_e32 v133, 0xffff0000, v86
	v_lshlrev_b32_e32 v134, 16, v87
	v_and_b32_e32 v135, 0xffff0000, v87
	v_pk_mul_f32 v[56:57], v[56:57], v[106:107] op_sel_hi:[1,0]
	v_pk_mul_f32 v[58:59], v[58:59], v[106:107] op_sel_hi:[1,0]
	v_pk_mul_f32 v[60:61], v[60:61], v[106:107] op_sel_hi:[1,0]
	v_pk_mul_f32 v[62:63], v[62:63], v[106:107] op_sel_hi:[1,0]
	v_pk_mul_f32 v[56:57], v[56:57], v[128:129]
	v_pk_mul_f32 v[58:59], v[58:59], v[130:131]
	v_pk_mul_f32 v[60:61], v[60:61], v[132:133]
	v_pk_mul_f32 v[62:63], v[62:63], v[134:135]
	v_cvt_pk_bf16_f32 v116, v56, v57
	v_cvt_pk_bf16_f32 v117, v58, v59
	v_cvt_pk_bf16_f32 v118, v60, v61
	v_cvt_pk_bf16_f32 v119, v62, v63
	global_store_dwordx4 v6, v[116:119], s[64:65]
	v_lshlrev_b32_e32 v128, 16, v88
	v_and_b32_e32 v129, 0xffff0000, v88
	v_lshlrev_b32_e32 v130, 16, v89
	v_and_b32_e32 v131, 0xffff0000, v89
	v_lshlrev_b32_e32 v132, 16, v90
	v_and_b32_e32 v133, 0xffff0000, v90
	v_lshlrev_b32_e32 v134, 16, v91
	v_and_b32_e32 v135, 0xffff0000, v91
	v_pk_mul_f32 v[64:65], v[64:65], v[108:109] op_sel_hi:[1,0]
	v_pk_mul_f32 v[66:67], v[66:67], v[108:109] op_sel_hi:[1,0]
	v_pk_mul_f32 v[68:69], v[68:69], v[108:109] op_sel_hi:[1,0]
	v_pk_mul_f32 v[70:71], v[70:71], v[108:109] op_sel_hi:[1,0]
	v_pk_mul_f32 v[64:65], v[64:65], v[128:129]
	v_pk_mul_f32 v[66:67], v[66:67], v[130:131]
	v_pk_mul_f32 v[68:69], v[68:69], v[132:133]
	v_pk_mul_f32 v[70:71], v[70:71], v[134:135]
	v_cvt_pk_bf16_f32 v120, v64, v65
	v_cvt_pk_bf16_f32 v121, v66, v67
	v_cvt_pk_bf16_f32 v122, v68, v69
	v_cvt_pk_bf16_f32 v123, v70, v71
	global_store_dwordx4 v7, v[120:123], s[64:65]
	v_lshlrev_b32_e32 v128, 16, v92
	v_and_b32_e32 v129, 0xffff0000, v92
	v_lshlrev_b32_e32 v130, 16, v93
	v_and_b32_e32 v131, 0xffff0000, v93
	v_lshlrev_b32_e32 v132, 16, v94
	v_and_b32_e32 v133, 0xffff0000, v94
	v_lshlrev_b32_e32 v134, 16, v95
	v_and_b32_e32 v135, 0xffff0000, v95
	v_pk_mul_f32 v[72:73], v[72:73], v[110:111] op_sel_hi:[1,0]
	v_pk_mul_f32 v[74:75], v[74:75], v[110:111] op_sel_hi:[1,0]
	v_pk_mul_f32 v[76:77], v[76:77], v[110:111] op_sel_hi:[1,0]
	v_pk_mul_f32 v[78:79], v[78:79], v[110:111] op_sel_hi:[1,0]
	v_pk_mul_f32 v[72:73], v[72:73], v[128:129]
	v_pk_mul_f32 v[74:75], v[74:75], v[130:131]
	v_pk_mul_f32 v[76:77], v[76:77], v[132:133]
	v_pk_mul_f32 v[78:79], v[78:79], v[134:135]
	v_cvt_pk_bf16_f32 v124, v72, v73
	v_cvt_pk_bf16_f32 v125, v74, v75
	v_cvt_pk_bf16_f32 v126, v76, v77
	v_cvt_pk_bf16_f32 v127, v78, v79
	global_store_dwordx4 v8, v[124:127], s[64:65]
	s_cmp_lt_u32 s70, s67
	s_cbranch_scc0 .Lgn_done
	s_mov_b32 s66, s70
	s_waitcnt vmcnt(4)
	s_branch .Lgn_top
.Lgn_done:
.LBB0_1418:
	s_or_b64 exec, exec, s[0:1]
	s_waitcnt vmcnt(0)
	s_barrier
	s_mov_b64 s[0:1], exec
	v_readlane_b32 s6, v254, 3
	v_readlane_b32 s7, v254, 4
	s_and_b64 s[6:7], s[0:1], s[6:7]
	s_xor_b64 s[0:1], s[6:7], s[0:1]
	s_mov_b64 exec, s[6:7]
	s_cbranch_execz .LBB0_1471
	s_add_i32 s6, 0, 0x22ff0
	v_mov_b32_e32 v0, s6
	s_waitcnt vmcnt(0) expcnt(0) lgkmcnt(0)
	ds_read_b32 v2, v0
	s_add_i32 s6, 0, 0x22ff4
	v_mov_b32_e32 v0, s6
	ds_read_b32 v0, v0
	s_waitcnt lgkmcnt(1)
	v_cmp_ne_u32_e32 vcc, 0, v2
	s_cbranch_vccnz .LBB0_1434
	v_readlane_b32 s6, v254, 0
	s_mul_i32 s33, s97, s6
	s_add_u32 s6, s94, 0x32c02a00
	s_addc_u32 s7, s95, 0
	s_add_u32 s8, s94, 0x32c02c00
	s_addc_u32 s9, s95, 0
	s_add_u32 s10, s94, 0x32c02d00
	s_addc_u32 s11, s95, 0
	s_add_u32 s14, s94, 0x32c02e00
	s_addc_u32 s15, s95, 0
	s_add_u32 s16, s94, 0x32c02f00
	s_addc_u32 s17, s95, 0
	s_add_u32 s18, s94, 0x32c03000
	s_addc_u32 s19, s95, 0
	s_add_u32 s20, s94, 0x32c03100
	s_addc_u32 s21, s95, 0
	s_add_u32 s22, s94, 0x32c03200
	s_addc_u32 s23, s95, 0
	s_add_u32 s24, s94, 0x32c03300
	s_addc_u32 s25, s95, 0
	s_add_u32 s26, s94, 0x32c03400
	s_addc_u32 s27, s95, 0
	s_add_u32 s28, s94, 0x32c03500
	s_addc_u32 s29, s95, 0
	s_add_u32 s30, s94, 0x32c03600
	s_addc_u32 s31, s95, 0
	s_add_u32 s34, s94, 0x32c03700
	s_addc_u32 s35, s95, 0
	s_add_u32 s36, s94, 0x32c03800
	s_addc_u32 s37, s95, 0
	s_add_u32 s38, s94, 0x32c03900
	s_addc_u32 s39, s95, 0
	s_add_u32 s40, s94, 0x32c03a00
	s_addc_u32 s41, s95, 0
	s_add_u32 s42, s94, 0x32c03b00
	s_mul_i32 s33, s33, s96
	s_addc_u32 s43, s95, 0
	s_mov_b32 s50, 1
	v_mov_b32_e32 v16, 0
	s_branch .LBB0_1422
